# HID as 128 slabs of 32 columns ([slab][T][32]): every FF1 epilogue store writes 1 KiB contiguous; FF2 A addressing adapted
# speedup vs baseline: 1.0220x; 1.0057x over previous
.LBB0_867:
	s_lshl_b32 s12, s12, 5
	s_and_b32 s18, s12, 0x60
	s_mov_b64 s[12:13], 0x80
	s_add_i32 m0, s35, 0x18000
	v_lshl_add_u64 v[6:7], v[6:7], 0, s[12:13]
	s_ashr_i32 s46, s92, 31
	s_lshl_b32 s15, s14, 13
	s_lshl_b32 s19, s18, 7
	s_waitcnt vmcnt(2)
	s_barrier
	global_load_lds_dwordx4 v[6:7], off
	v_lshl_add_u64 v[4:5], v[4:5], 0, s[12:13]
	s_add_i32 m0, s35, 0x1a000
	s_add_i32 s47, s35, 0x8000
	s_add_i32 s48, s35, 0xa000
	global_load_lds_dwordx4 v[4:5], off
	v_lshl_add_u64 v[0:1], v[0:1], 0, s[12:13]
	s_mov_b32 m0, s47
	s_add_u32 s16, s38, 0x40080
	global_load_lds_dwordx4 v[0:1], off
	v_lshl_add_u64 v[0:1], v[2:3], 0, s[12:13]
	s_mov_b32 m0, s48
	s_addc_u32 s17, s39, 0
	global_load_lds_dwordx4 v[0:1], off
	s_add_i32 m0, s35, 0x1c000
	v_lshl_add_u64 v[0:1], s[16:17], 0, v[130:131]
	global_load_lds_dwordx4 v[0:1], off
	v_lshl_add_u64 v[0:1], s[16:17], 0, v[134:135]
	s_add_i32 m0, s35, 0x1e000
	s_sext_i32_i8 s56, s4
	global_load_lds_dwordx4 v[0:1], off
	v_and_b32_e32 v0, 15, v220
	v_lshlrev_b32_e32 v1, 1, v11
	v_lshlrev_b32_e32 v2, 6, v220
	s_movk_i32 s4, 0x3c0
	v_lshlrev_b32_e32 v3, 2, v220
	v_and_or_b32 v2, v2, s4, v1
	v_and_b32_e32 v3, 32, v3
	v_lshl_or_b32 v144, s14, 6, v0
	v_lshl_or_b32 v0, v0, 6, v1
	v_lshlrev_b32_e32 v1, 8, v220
	v_bitop3_b32 v145, s19, v2, v3 bitop3:0xf6
	v_and_b32_e32 v1, 0x38000, v1
	v_lshlrev_b32_e32 v2, 11, v10
	v_or3_b32 v1, v8, v1, v2
	v_add_u32_e32 v136, v1, v9
	v_lshlrev_b32_e32 v1, 4, v12
	s_waitcnt vmcnt(6)
	s_cmpk_lt_u32 s5, 0x100
	v_and_b32_e32 v1, 0x78000, v1
	v_bitop3_b32 v0, v0, s15, v3 bitop3:0xde
	s_cselect_b64 s[14:15], -1, 0
	v_or3_b32 v1, v8, v1, v2
	s_add_i32 s50, 0, 0x10000
	s_add_i32 s51, 0, 0x14000
	s_mov_b32 s49, s92
	v_or_b32_e32 v146, s18, v11
	v_mov_b32_e32 v137, v131
	v_add_u32_e32 v138, v1, v9
	v_mov_b32_e32 v139, v131
	v_mov_b64_e32 v[140:141], 0x800
	v_mov_b64_e32 v[142:143], 0x7ff
	v_add_u32_e32 v147, s50, v145
	v_add_u32_e32 v148, s51, v145
	v_add_u32_e32 v149, 0, v0
	s_mov_b64 s[16:17], 0x802000
	s_mov_b32 s52, 0x2000
	s_mov_b64 s[18:19], 0x802400
	s_mov_b32 s53, 0x2400
	s_mov_b64 s[20:21], 0x802800
	s_mov_b32 s54, 0x2800
	s_mov_b64 s[22:23], 0x802c00
	s_mov_b32 s55, 0x2c00
	s_mov_b64 s[98:99], 0x800000
	s_barrier
	s_branch .LBB0_870

.LBB0_880:
	v_lshl_add_u32 v150, s34, 8, v144
	v_lshl_or_b32 v152, s56, 8, v146
	v_ashrrev_i32_e32 v151, 31, v150
	v_max_f32_e32 v124, 0, v124
	v_max_f32_e32 v120, 0, v120
	v_max_f32_e32 v125, 0, v125
	v_max_f32_e32 v121, 0, v121
	v_max_f32_e32 v126, 0, v126
	v_max_f32_e32 v127, 0, v127
	v_ashrrev_i32_e32 v153, 31, v152
	v_lshlrev_b64 v[154:155], 6, v[150:151]
	v_pk_mul_f32 v[124:125], v[124:125], v[124:125]
	v_pk_mul_f32 v[120:121], v[120:121], v[120:121]
	v_max_f32_e32 v122, 0, v122
	v_max_f32_e32 v123, 0, v123
	v_pk_mul_f32 v[126:127], v[126:127], v[126:127]
	v_pk_mul_f32 v[156:157], v[122:123], v[122:123]
	v_cvt_pk_bf16_f32 v122, v124, v125
	v_cvt_pk_bf16_f32 v123, v126, v127
	v_cvt_pk_bf16_f32 v124, v120, v121
	v_lshl_add_u64 v[120:121], s[78:79], 0, v[154:155]
	v_and_b32_e32 v126, 0xfe0, v152
	v_and_b32_e32 v127, 31, v152
	v_lshlrev_b32_e32 v126, 16, v126
	v_lshl_or_b32 v126, v127, 1, v126
	v_mov_b32_e32 v127, 0
	v_cvt_pk_bf16_f32 v125, v156, v157
	v_lshl_add_u64 v[120:121], v[120:121], 0, v[126:127]
	v_max_f32_e32 v112, 0, v112
	v_max_f32_e32 v113, 0, v113
	global_store_dwordx4 v[120:121], v[122:125], off
	s_nop 1
	v_pk_mul_f32 v[122:123], v[112:113], v[112:113]
	v_max_f32_e32 v114, 0, v114
	v_max_f32_e32 v116, 0, v116
	v_max_f32_e32 v117, 0, v117
	v_max_f32_e32 v112, 0, v118
	v_max_f32_e32 v113, 0, v119
	v_max_f32_e32 v115, 0, v115
	v_pk_mul_f32 v[116:117], v[116:117], v[116:117]
	v_pk_mul_f32 v[118:119], v[112:113], v[112:113]
	v_pk_mul_f32 v[124:125], v[114:115], v[114:115]
	v_cvt_pk_bf16_f32 v112, v116, v117
	v_cvt_pk_bf16_f32 v113, v118, v119
	v_cvt_pk_bf16_f32 v114, v122, v123
	v_cvt_pk_bf16_f32 v115, v124, v125
	v_max_f32_e32 v104, 0, v104
	v_max_f32_e32 v105, 0, v105
	v_lshl_add_u64 v[200:201], v[120:121], 0, s[98:99]
	global_store_dwordx4 v[200:201], v[112:115], off
	s_nop 1
	v_or_b32_e32 v112, 16, v150
	v_pk_mul_f32 v[114:115], v[104:105], v[104:105]
	v_ashrrev_i32_e32 v113, 31, v112
	v_max_f32_e32 v108, 0, v108
	v_max_f32_e32 v109, 0, v109
	v_max_f32_e32 v106, 0, v106
	v_lshlrev_b64 v[112:113], 6, v[112:113]
	v_pk_mul_f32 v[108:109], v[108:109], v[108:109]
	v_max_f32_e32 v104, 0, v110
	v_max_f32_e32 v105, 0, v111
	v_max_f32_e32 v107, 0, v107
	v_pk_mul_f32 v[110:111], v[104:105], v[104:105]
	v_pk_mul_f32 v[116:117], v[106:107], v[106:107]
	v_cvt_pk_bf16_f32 v104, v108, v109
	v_lshl_add_u64 v[108:109], s[78:79], 0, v[112:113]
	v_cvt_pk_bf16_f32 v105, v110, v111
	v_cvt_pk_bf16_f32 v106, v114, v115
	v_cvt_pk_bf16_f32 v107, v116, v117
	v_lshl_add_u64 v[108:109], v[108:109], 0, v[126:127]
	v_max_f32_e32 v96, 0, v96
	v_max_f32_e32 v97, 0, v97
	global_store_dwordx4 v[108:109], v[104:107], off
	s_nop 1
	v_pk_mul_f32 v[104:105], v[96:97], v[96:97]
	v_max_f32_e32 v98, 0, v98
	v_max_f32_e32 v100, 0, v100
	v_max_f32_e32 v101, 0, v101
	v_max_f32_e32 v96, 0, v102
	v_max_f32_e32 v97, 0, v103
	v_max_f32_e32 v99, 0, v99
	v_pk_mul_f32 v[100:101], v[100:101], v[100:101]
	v_pk_mul_f32 v[102:103], v[96:97], v[96:97]
	v_pk_mul_f32 v[106:107], v[98:99], v[98:99]
	v_cvt_pk_bf16_f32 v96, v100, v101
	v_cvt_pk_bf16_f32 v97, v102, v103
	v_cvt_pk_bf16_f32 v98, v104, v105
	v_cvt_pk_bf16_f32 v99, v106, v107
	v_max_f32_e32 v88, 0, v88
	v_max_f32_e32 v89, 0, v89
	v_lshl_add_u64 v[202:203], v[108:109], 0, s[98:99]
	global_store_dwordx4 v[202:203], v[96:99], off
	s_nop 1
	v_or_b32_e32 v96, 32, v150
	v_pk_mul_f32 v[98:99], v[88:89], v[88:89]
	v_ashrrev_i32_e32 v97, 31, v96
	v_max_f32_e32 v92, 0, v92
	v_max_f32_e32 v93, 0, v93
	v_max_f32_e32 v90, 0, v90
	v_lshlrev_b64 v[96:97], 6, v[96:97]
	v_pk_mul_f32 v[92:93], v[92:93], v[92:93]
	v_max_f32_e32 v88, 0, v94
	v_max_f32_e32 v89, 0, v95
	v_max_f32_e32 v91, 0, v91
	v_pk_mul_f32 v[94:95], v[88:89], v[88:89]
	v_pk_mul_f32 v[100:101], v[90:91], v[90:91]
	v_cvt_pk_bf16_f32 v88, v92, v93
	v_lshl_add_u64 v[92:93], s[78:79], 0, v[96:97]
	v_cvt_pk_bf16_f32 v89, v94, v95
	v_cvt_pk_bf16_f32 v90, v98, v99
	v_cvt_pk_bf16_f32 v91, v100, v101
	v_lshl_add_u64 v[92:93], v[92:93], 0, v[126:127]
	v_max_f32_e32 v80, 0, v80
	v_max_f32_e32 v81, 0, v81
	global_store_dwordx4 v[92:93], v[88:91], off
	s_nop 1
	v_pk_mul_f32 v[88:89], v[80:81], v[80:81]
	v_max_f32_e32 v82, 0, v82
	v_max_f32_e32 v84, 0, v84
	v_max_f32_e32 v85, 0, v85
	v_max_f32_e32 v80, 0, v86
	v_max_f32_e32 v81, 0, v87
	v_max_f32_e32 v83, 0, v83
	v_pk_mul_f32 v[84:85], v[84:85], v[84:85]
	v_pk_mul_f32 v[86:87], v[80:81], v[80:81]
	v_pk_mul_f32 v[90:91], v[82:83], v[82:83]
	v_cvt_pk_bf16_f32 v80, v84, v85
	v_cvt_pk_bf16_f32 v81, v86, v87
	v_cvt_pk_bf16_f32 v82, v88, v89
	v_cvt_pk_bf16_f32 v83, v90, v91
	v_max_f32_e32 v72, 0, v72
	v_max_f32_e32 v73, 0, v73
	v_lshl_add_u64 v[204:205], v[92:93], 0, s[98:99]
	global_store_dwordx4 v[204:205], v[80:83], off
	s_nop 1
	v_or_b32_e32 v80, 48, v150
	v_pk_mul_f32 v[82:83], v[72:73], v[72:73]
	v_ashrrev_i32_e32 v81, 31, v80
	v_max_f32_e32 v76, 0, v76
	v_max_f32_e32 v77, 0, v77
	v_max_f32_e32 v74, 0, v74
	v_lshlrev_b64 v[80:81], 6, v[80:81]
	v_pk_mul_f32 v[76:77], v[76:77], v[76:77]
	v_max_f32_e32 v72, 0, v78
	v_max_f32_e32 v73, 0, v79
	v_max_f32_e32 v75, 0, v75
	v_pk_mul_f32 v[78:79], v[72:73], v[72:73]
	v_pk_mul_f32 v[84:85], v[74:75], v[74:75]
	v_cvt_pk_bf16_f32 v72, v76, v77
	v_lshl_add_u64 v[76:77], s[78:79], 0, v[80:81]
	v_cvt_pk_bf16_f32 v73, v78, v79
	v_cvt_pk_bf16_f32 v74, v82, v83
	v_cvt_pk_bf16_f32 v75, v84, v85
	v_lshl_add_u64 v[76:77], v[76:77], 0, v[126:127]
	v_max_f32_e32 v64, 0, v64
	v_max_f32_e32 v65, 0, v65
	global_store_dwordx4 v[76:77], v[72:75], off
	s_nop 1
	v_pk_mul_f32 v[72:73], v[64:65], v[64:65]
	v_max_f32_e32 v66, 0, v66
	v_max_f32_e32 v68, 0, v68
	v_max_f32_e32 v69, 0, v69
	v_max_f32_e32 v64, 0, v70
	v_max_f32_e32 v65, 0, v71
	v_max_f32_e32 v67, 0, v67
	v_pk_mul_f32 v[68:69], v[68:69], v[68:69]
	v_pk_mul_f32 v[70:71], v[64:65], v[64:65]
	v_pk_mul_f32 v[74:75], v[66:67], v[66:67]
	v_cvt_pk_bf16_f32 v64, v68, v69
	v_cvt_pk_bf16_f32 v65, v70, v71
	v_cvt_pk_bf16_f32 v66, v72, v73
	v_cvt_pk_bf16_f32 v67, v74, v75
	v_max_f32_e32 v56, 0, v56
	v_max_f32_e32 v57, 0, v57
	v_lshl_add_u64 v[206:207], v[76:77], 0, s[98:99]
	global_store_dwordx4 v[206:207], v[64:67], off
	s_nop 1
	v_pk_mul_f32 v[64:65], v[56:57], v[56:57]
	v_max_f32_e32 v58, 0, v58
	v_max_f32_e32 v56, 0, v62
	v_max_f32_e32 v57, 0, v63
	v_max_f32_e32 v60, 0, v60
	v_max_f32_e32 v61, 0, v61
	v_max_f32_e32 v59, 0, v59
	v_pk_mul_f32 v[62:63], v[56:57], v[56:57]
	v_pk_mul_f32 v[60:61], v[60:61], v[60:61]
	v_pk_mul_f32 v[66:67], v[58:59], v[58:59]
	v_cvt_pk_bf16_f32 v57, v62, v63
	v_add_co_u32_e32 v62, vcc, s52, v120
	v_cvt_pk_bf16_f32 v56, v60, v61
	v_cvt_pk_bf16_f32 v58, v64, v65
	v_cvt_pk_bf16_f32 v59, v66, v67
	v_addc_co_u32_e32 v63, vcc, 0, v121, vcc
	v_max_f32_e32 v48, 0, v48
	v_max_f32_e32 v49, 0, v49
	global_store_dwordx4 v[62:63], v[56:59], off
	s_nop 1
	v_pk_mul_f32 v[56:57], v[48:49], v[48:49]
	v_max_f32_e32 v50, 0, v50
	v_max_f32_e32 v52, 0, v52
	v_max_f32_e32 v53, 0, v53
	v_max_f32_e32 v48, 0, v54
	v_max_f32_e32 v49, 0, v55
	v_max_f32_e32 v51, 0, v51
	v_pk_mul_f32 v[52:53], v[52:53], v[52:53]
	v_pk_mul_f32 v[54:55], v[48:49], v[48:49]
	v_pk_mul_f32 v[58:59], v[50:51], v[50:51]
	v_lshl_add_u64 v[60:61], v[120:121], 0, s[16:17]
	v_cvt_pk_bf16_f32 v48, v52, v53
	v_cvt_pk_bf16_f32 v49, v54, v55
	v_cvt_pk_bf16_f32 v50, v56, v57
	v_cvt_pk_bf16_f32 v51, v58, v59
	v_max_f32_e32 v40, 0, v40
	v_max_f32_e32 v41, 0, v41
	global_store_dwordx4 v[60:61], v[48:51], off
	s_nop 1
	v_pk_mul_f32 v[48:49], v[40:41], v[40:41]
	v_max_f32_e32 v42, 0, v42
	v_max_f32_e32 v40, 0, v46
	v_max_f32_e32 v41, 0, v47
	v_max_f32_e32 v44, 0, v44
	v_max_f32_e32 v45, 0, v45
	v_max_f32_e32 v43, 0, v43
	v_pk_mul_f32 v[46:47], v[40:41], v[40:41]
	v_pk_mul_f32 v[44:45], v[44:45], v[44:45]
	v_pk_mul_f32 v[50:51], v[42:43], v[42:43]
	v_cvt_pk_bf16_f32 v41, v46, v47
	v_add_co_u32_e32 v46, vcc, s53, v120
	v_cvt_pk_bf16_f32 v40, v44, v45
	v_cvt_pk_bf16_f32 v42, v48, v49
	v_cvt_pk_bf16_f32 v43, v50, v51
	v_addc_co_u32_e32 v47, vcc, 0, v121, vcc
	v_max_f32_e32 v32, 0, v32
	v_max_f32_e32 v33, 0, v33
	global_store_dwordx4 v[46:47], v[40:43], off
	s_nop 1
	v_pk_mul_f32 v[40:41], v[32:33], v[32:33]
	v_max_f32_e32 v34, 0, v34
	v_max_f32_e32 v36, 0, v36
	v_max_f32_e32 v37, 0, v37
	v_max_f32_e32 v32, 0, v38
	v_max_f32_e32 v33, 0, v39
	v_max_f32_e32 v35, 0, v35
	v_pk_mul_f32 v[36:37], v[36:37], v[36:37]
	v_pk_mul_f32 v[38:39], v[32:33], v[32:33]
	v_pk_mul_f32 v[42:43], v[34:35], v[34:35]
	v_lshl_add_u64 v[44:45], v[120:121], 0, s[18:19]
	v_cvt_pk_bf16_f32 v32, v36, v37
	v_cvt_pk_bf16_f32 v33, v38, v39
	v_cvt_pk_bf16_f32 v34, v40, v41
	v_cvt_pk_bf16_f32 v35, v42, v43
	v_max_f32_e32 v24, 0, v24
	v_max_f32_e32 v25, 0, v25
	global_store_dwordx4 v[44:45], v[32:35], off
	s_nop 1
	v_pk_mul_f32 v[32:33], v[24:25], v[24:25]
	v_max_f32_e32 v26, 0, v26
	v_max_f32_e32 v24, 0, v30
	v_max_f32_e32 v25, 0, v31
	v_max_f32_e32 v28, 0, v28
	v_max_f32_e32 v29, 0, v29
	v_max_f32_e32 v27, 0, v27
	v_pk_mul_f32 v[30:31], v[24:25], v[24:25]
	v_pk_mul_f32 v[28:29], v[28:29], v[28:29]
	v_pk_mul_f32 v[34:35], v[26:27], v[26:27]
	v_cvt_pk_bf16_f32 v25, v30, v31
	v_add_co_u32_e32 v30, vcc, s54, v120
	v_cvt_pk_bf16_f32 v24, v28, v29
	v_cvt_pk_bf16_f32 v26, v32, v33
	v_cvt_pk_bf16_f32 v27, v34, v35
	v_addc_co_u32_e32 v31, vcc, 0, v121, vcc
	v_max_f32_e32 v16, 0, v16
	v_max_f32_e32 v17, 0, v17
	global_store_dwordx4 v[30:31], v[24:27], off
	s_nop 1
	v_pk_mul_f32 v[24:25], v[16:17], v[16:17]
	v_max_f32_e32 v18, 0, v18
	v_max_f32_e32 v20, 0, v20
	v_max_f32_e32 v21, 0, v21
	v_max_f32_e32 v16, 0, v22
	v_max_f32_e32 v17, 0, v23
	v_max_f32_e32 v19, 0, v19
	v_pk_mul_f32 v[20:21], v[20:21], v[20:21]
	v_pk_mul_f32 v[22:23], v[16:17], v[16:17]
	v_pk_mul_f32 v[26:27], v[18:19], v[18:19]
	v_lshl_add_u64 v[28:29], v[120:121], 0, s[20:21]
	v_cvt_pk_bf16_f32 v16, v20, v21
	v_cvt_pk_bf16_f32 v17, v22, v23
	v_cvt_pk_bf16_f32 v18, v24, v25
	v_cvt_pk_bf16_f32 v19, v26, v27
	v_max_f32_e32 v8, 0, v8
	v_max_f32_e32 v9, 0, v9
	global_store_dwordx4 v[28:29], v[16:19], off
	s_nop 1
	v_pk_mul_f32 v[16:17], v[8:9], v[8:9]
	v_max_f32_e32 v10, 0, v10
	v_max_f32_e32 v8, 0, v14
	v_max_f32_e32 v9, 0, v15
	v_max_f32_e32 v12, 0, v12
	v_max_f32_e32 v13, 0, v13
	v_max_f32_e32 v11, 0, v11
	v_pk_mul_f32 v[14:15], v[8:9], v[8:9]
	v_pk_mul_f32 v[12:13], v[12:13], v[12:13]
	v_pk_mul_f32 v[18:19], v[10:11], v[10:11]
	v_cvt_pk_bf16_f32 v9, v14, v15
	v_add_co_u32_e32 v14, vcc, s55, v120
	v_cvt_pk_bf16_f32 v8, v12, v13
	v_cvt_pk_bf16_f32 v10, v16, v17
	v_cvt_pk_bf16_f32 v11, v18, v19
	v_addc_co_u32_e32 v15, vcc, 0, v121, vcc
	v_max_f32_e32 v0, 0, v0
	v_max_f32_e32 v1, 0, v1
	global_store_dwordx4 v[14:15], v[8:11], off
	s_nop 1
	v_pk_mul_f32 v[8:9], v[0:1], v[0:1]
	v_max_f32_e32 v2, 0, v2
	v_max_f32_e32 v4, 0, v4
	v_max_f32_e32 v5, 0, v5
	v_max_f32_e32 v0, 0, v6
	v_max_f32_e32 v1, 0, v7
	v_max_f32_e32 v3, 0, v3
	v_pk_mul_f32 v[4:5], v[4:5], v[4:5]
	v_pk_mul_f32 v[6:7], v[0:1], v[0:1]
	v_pk_mul_f32 v[10:11], v[2:3], v[2:3]
	v_lshl_add_u64 v[12:13], v[120:121], 0, s[22:23]
	v_cvt_pk_bf16_f32 v0, v4, v5
	v_cvt_pk_bf16_f32 v1, v6, v7
	v_cvt_pk_bf16_f32 v2, v8, v9
	v_cvt_pk_bf16_f32 v3, v10, v11
	s_andn2_b64 vcc, exec, s[4:5]
	s_mov_b64 s[4:5], -1
	global_store_dwordx4 v[12:13], v[0:3], off
	s_cbranch_vccnz .LBB0_869
	s_andn2_b64 vcc, exec, s[6:7]
	s_cbranch_vccnz .LBB0_868
	s_barrier
	s_branch .LBB0_868

.LBB0_941:
	s_andn2_b64 vcc, exec, s[4:5]
	s_cbranch_vccnz .LBB0_977
	s_waitcnt vmcnt(0)
	v_lshrrev_b32_e32 v2, 1, v220
	v_lshrrev_b32_e32 v3, 5, v220
	v_and_b32_e32 v2, 24, v2
	v_and_b32_e32 v3, 4, v3
	v_bfe_u32 v4, v220, 2, 2
	v_lshlrev_b32_e32 v0, 4, v220
	v_and_b32_e32 v1, 32, v220
	v_bfe_u32 v10, v220, 2, 4
	v_or3_b32 v2, v3, v4, v2
	v_lshrrev_b32_e32 v3, 3, v220
	s_movk_i32 s3, 0x70
	v_bitop3_b32 v8, v0, v1, 48 bitop3:0x6c
	v_and_b32_e32 v9, 64, v220
	v_and_or_b32 v4, v3, s3, v10
	s_movk_i32 s3, 0x60
	v_add_u32_e32 v11, 0x2000, v0
	v_or_b32_e32 v1, v8, v9
	v_and_or_b32 v3, v3, s3, v2
	v_lshrrev_b32_e32 v0, 7, v11
	s_movk_i32 s3, 0xf0
	v_lshl_or_b32 v130, v3, 13, v1
	v_and_or_b32 v3, v0, s3, v10
	s_movk_i32 s3, 0xe0
	s_lshr_b32 s4, s6, 6
	s_ashr_i32 s31, s30, 31
	s_ashr_i32 s15, s14, 31
	v_and_or_b32 v0, v0, s3, v2
	s_lshr_b32 s7, s6, 8
	s_lshl_b32 s3, s4, 10
	s_lshl_b64 s[16:17], s[30:31], 14
	s_lshl_b64 s[18:19], s[14:15], 21
	s_add_u32 s36, s70, s18
	s_addc_u32 s37, s71, s19
	s_add_i32 s33, s3, 0
	s_add_i32 m0, s33, 0x10000
	v_lshl_or_b32 v134, v0, 13, v1
	global_load_lds_dwordx4 v130, s[36:37]
	s_add_i32 m0, s33, 0x12000
	s_add_u32 s18, s36, 0x100000
	global_load_lds_dwordx4 v134, s[36:37]
	s_addc_u32 s19, s37, 0
	s_add_i32 m0, s33, 0x14000
	v_lshlrev_b32_e32 v128, 15, v9
	v_or_b32_e32 v128, v128, v8
	v_lshl_or_b32 v128, v4, 6, v128
	global_load_lds_dwordx4 v130, s[18:19]
	s_add_i32 m0, s33, 0x16000
	s_add_u32 s34, s78, s16
	s_addc_u32 s35, s79, s17
	s_add_i32 s40, s33, 0x2000
	global_load_lds_dwordx4 v134, s[18:19]
	s_mov_b32 m0, s33
	s_add_u32 s16, s34, 0x2000
	v_lshlrev_b32_e32 v132, 15, v9
	v_or_b32_e32 v132, v132, v8
	v_lshl_or_b32 v132, v3, 6, v132
	global_load_lds_dwordx4 v128, s[34:35]
	s_mov_b32 m0, s40
	s_addc_u32 s17, s35, 0
	s_add_i32 s41, s33, 0x4000
	global_load_lds_dwordx4 v132, s[34:35]
	s_mov_b32 m0, s41
	s_add_i32 s42, s33, 0x6000
	global_load_lds_dwordx4 v128, s[16:17]
	s_mov_b32 m0, s42
	v_mov_b32_e32 v131, 0
	global_load_lds_dwordx4 v132, s[16:17]
	v_mov_b32_e32 v135, v131
	v_mov_b32_e32 v129, v131
	v_mov_b32_e32 v133, v131
	s_cmp_eq_u32 s7, 1
	s_mov_b32 s15, 0
	v_lshl_add_u64 v[6:7], s[36:37], 0, v[130:131]
	s_waitcnt lgkmcnt(0)
	v_lshl_add_u64 v[4:5], s[36:37], 0, v[134:135]
	v_lshl_add_u64 v[0:1], s[34:35], 0, v[128:129]
	s_cselect_b64 s[16:17], -1, 0
	s_cmp_lg_u32 s7, 1
	v_lshl_add_u64 v[2:3], s[34:35], 0, v[132:133]
	s_cbranch_scc1 .LBB0_944
	s_barrier
.LBB0_944:
	s_mov_b64 s[18:19], 0x80
	s_mov_b64 s[98:99], 0x400000
	s_and_b32 s45, s4, 3
	s_add_i32 m0, s33, 0x18000
	v_lshl_add_u64 v[6:7], v[6:7], 0, s[18:19]
	s_ashr_i32 s43, s92, 31
	s_ashr_i32 s44, s2, 31
	s_lshl_b32 s20, s7, 13
	s_lshl_b32 s21, s45, 12
	s_waitcnt vmcnt(2)
	s_barrier
	global_load_lds_dwordx4 v[6:7], off
	v_lshl_add_u64 v[4:5], v[4:5], 0, s[18:19]
	s_add_i32 m0, s33, 0x1a000
	s_add_i32 s46, s33, 0x8000
	s_add_i32 s47, s33, 0xa000
	global_load_lds_dwordx4 v[4:5], off
	v_lshl_add_u64 v[0:1], v[0:1], 0, s[98:99]
	s_mov_b32 m0, s46
	s_add_u32 s4, s36, 0x100080
	global_load_lds_dwordx4 v[0:1], off
	v_lshl_add_u64 v[0:1], v[2:3], 0, s[98:99]
	s_mov_b32 m0, s47
	s_addc_u32 s5, s37, 0
	global_load_lds_dwordx4 v[0:1], off
	s_add_i32 m0, s33, 0x1c000
	v_lshl_add_u64 v[0:1], s[4:5], 0, v[130:131]
	global_load_lds_dwordx4 v[0:1], off
	v_lshl_add_u64 v[0:1], s[4:5], 0, v[134:135]
	s_add_i32 m0, s33, 0x1e000
	v_lshlrev_b32_e32 v4, 6, v220
	global_load_lds_dwordx4 v[0:1], off
	v_bfe_u32 v0, v220, 4, 2
	v_and_b32_e32 v1, 15, v220
	v_lshlrev_b32_e32 v3, 4, v0
	s_movk_i32 s4, 0x3c0
	v_lshlrev_b32_e32 v2, 3, v0
	v_and_or_b32 v4, v4, s4, v3
	v_cmp_eq_u32_e64 s[4:5], 0, v0
	v_lshl_or_b32 v148, s7, 6, v1
	v_lshl_or_b32 v0, v1, 6, v3
	v_lshlrev_b32_e32 v1, 3, v220
	v_lshl_or_b32 v150, s45, 5, v2
	v_and_b32_e32 v1, 0x1c00, v1
	v_lshlrev_b32_e32 v2, 6, v10
	v_lshlrev_b32_e32 v5, 2, v220
	v_or3_b32 v1, v8, v1, v2
	v_and_b32_e32 v5, 32, v5
	v_lshl_add_u32 v136, v9, 15, v1
	v_lshrrev_b32_e32 v1, 1, v11
	v_bitop3_b32 v0, v0, s20, v5 bitop3:0xde
	s_waitcnt vmcnt(6)
	s_cmpk_lt_u32 s6, 0x100
	v_and_b32_e32 v1, 0x3c00, v1
	v_bitop3_b32 v149, s21, v4, v5 bitop3:0xf6
	s_cselect_b64 s[20:21], -1, 0
	v_or3_b32 v1, v8, v1, v2
	s_add_i32 s49, 0, 0x10000
	s_add_i32 s50, 0, 0x14000
	v_add_u32_e32 v153, 0, v0
	v_mbcnt_lo_u32_b32 v0, -1, 0
	s_mov_b32 s48, s92
	v_mov_b32_e32 v137, v131
	v_lshl_add_u32 v138, v9, 15, v1
	v_mov_b32_e32 v139, v131
	v_mov_b64_e32 v[140:141], 0x200
	v_mov_b64_e32 v[142:143], 0x1ff
	v_add_u32_e32 v151, s49, v149
	v_add_u32_e32 v152, s50, v149
	v_mbcnt_hi_u32_b32 v154, -1, v0
	s_mov_b32 s51, 0
	s_barrier
	s_branch .LBB0_947

.LBB0_953:
	s_ashr_i32 s25, s24, 31
	s_lshl_b64 s[26:27], s[24:25], 14
	s_add_u32 s26, s78, s26
	s_addc_u32 s27, s79, s27
	s_and_b64 s[28:29], s[6:7], exec
	s_cselect_b32 s25, s27, s35
	s_cselect_b32 s31, s26, s34
	s_ashr_i32 s23, s22, 31
	s_lshl_b64 s[28:29], s[22:23], 21
	s_add_u32 s28, s70, s28
	s_addc_u32 s29, s71, s29
	s_and_b64 s[38:39], s[6:7], exec
	s_cselect_b32 s23, s29, s37
	s_cselect_b32 s52, s28, s36
	s_add_u32 s34, s34, 0x402000
	s_addc_u32 s35, s35, 0
	s_add_u32 s53, s36, 0x100
	v_mov_b32_e32 v0, 0
	s_addc_u32 s54, s37, 0
	s_mov_b32 s55, -2
	v_mov_b32_e32 v1, v0
	v_mov_b32_e32 v2, v0
	v_mov_b32_e32 v3, v0
	v_mov_b32_e32 v4, v0
	s_waitcnt lgkmcnt(0)
	v_mov_b32_e32 v5, v0
	v_mov_b32_e32 v6, v0
	v_mov_b32_e32 v7, v0
	v_mov_b32_e32 v16, v0
	v_mov_b32_e32 v17, v0
	v_mov_b32_e32 v18, v0
	v_mov_b32_e32 v19, v0
	v_mov_b32_e32 v20, v0
	v_mov_b32_e32 v21, v0
	v_mov_b32_e32 v22, v0
	v_mov_b32_e32 v23, v0
	v_mov_b32_e32 v32, v0
	v_mov_b32_e32 v33, v0
	v_mov_b32_e32 v34, v0
	v_mov_b32_e32 v35, v0
	v_mov_b32_e32 v36, v0
	v_mov_b32_e32 v37, v0
	v_mov_b32_e32 v38, v0
	v_mov_b32_e32 v39, v0
	v_mov_b32_e32 v48, v0
	v_mov_b32_e32 v49, v0
	v_mov_b32_e32 v50, v0
	v_mov_b32_e32 v51, v0
	v_mov_b32_e32 v52, v0
	v_mov_b32_e32 v53, v0
	v_mov_b32_e32 v54, v0
	v_mov_b32_e32 v55, v0
	v_mov_b32_e32 v8, v0
	v_mov_b32_e32 v9, v0
	v_mov_b32_e32 v10, v0
	v_mov_b32_e32 v11, v0
	v_mov_b32_e32 v12, v0
	v_mov_b32_e32 v13, v0
	v_mov_b32_e32 v14, v0
	v_mov_b32_e32 v15, v0
	v_mov_b32_e32 v24, v0
	v_mov_b32_e32 v25, v0
	v_mov_b32_e32 v26, v0
	v_mov_b32_e32 v27, v0
	v_mov_b32_e32 v28, v0
	v_mov_b32_e32 v29, v0
	v_mov_b32_e32 v30, v0
	v_mov_b32_e32 v31, v0
	v_mov_b32_e32 v40, v0
	v_mov_b32_e32 v41, v0
	v_mov_b32_e32 v42, v0
	v_mov_b32_e32 v43, v0
	v_mov_b32_e32 v44, v0
	v_mov_b32_e32 v45, v0
	v_mov_b32_e32 v46, v0
	v_mov_b32_e32 v47, v0
	v_mov_b32_e32 v56, v0
	v_mov_b32_e32 v57, v0
	v_mov_b32_e32 v58, v0
	v_mov_b32_e32 v59, v0
	v_mov_b32_e32 v60, v0
	v_mov_b32_e32 v61, v0
	v_mov_b32_e32 v62, v0
	v_mov_b32_e32 v63, v0
	v_mov_b32_e32 v64, v0
	v_mov_b32_e32 v65, v0
	v_mov_b32_e32 v66, v0
	v_mov_b32_e32 v67, v0
	v_mov_b32_e32 v68, v0
	v_mov_b32_e32 v69, v0
	v_mov_b32_e32 v70, v0
	v_mov_b32_e32 v71, v0
	v_mov_b32_e32 v80, v0
	v_mov_b32_e32 v81, v0
	v_mov_b32_e32 v82, v0
	v_mov_b32_e32 v83, v0
	v_mov_b32_e32 v84, v0
	v_mov_b32_e32 v85, v0
	v_mov_b32_e32 v86, v0
	v_mov_b32_e32 v87, v0
	v_mov_b32_e32 v96, v0
	v_mov_b32_e32 v97, v0
	v_mov_b32_e32 v98, v0
	v_mov_b32_e32 v99, v0
	v_mov_b32_e32 v100, v0
	v_mov_b32_e32 v101, v0
	v_mov_b32_e32 v102, v0
	v_mov_b32_e32 v103, v0
	v_mov_b32_e32 v112, v0
	v_mov_b32_e32 v113, v0
	v_mov_b32_e32 v114, v0
	v_mov_b32_e32 v115, v0
	v_mov_b32_e32 v116, v0
	v_mov_b32_e32 v117, v0
	v_mov_b32_e32 v118, v0
	v_mov_b32_e32 v119, v0
	v_mov_b32_e32 v72, v0
	v_mov_b32_e32 v73, v0
	v_mov_b32_e32 v74, v0
	v_mov_b32_e32 v75, v0
	v_mov_b32_e32 v76, v0
	v_mov_b32_e32 v77, v0
	v_mov_b32_e32 v78, v0
	v_mov_b32_e32 v79, v0
	v_mov_b32_e32 v88, v0
	v_mov_b32_e32 v89, v0
	v_mov_b32_e32 v90, v0
	v_mov_b32_e32 v91, v0
	v_mov_b32_e32 v92, v0
	v_mov_b32_e32 v93, v0
	v_mov_b32_e32 v94, v0
	v_mov_b32_e32 v95, v0
	v_mov_b32_e32 v104, v0
	v_mov_b32_e32 v105, v0
	v_mov_b32_e32 v106, v0
	v_mov_b32_e32 v107, v0
	v_mov_b32_e32 v108, v0
	v_mov_b32_e32 v109, v0
	v_mov_b32_e32 v110, v0
	v_mov_b32_e32 v111, v0
	v_mov_b32_e32 v120, v0
	v_mov_b32_e32 v121, v0
	v_mov_b32_e32 v122, v0
	v_mov_b32_e32 v123, v0
	v_mov_b32_e32 v124, v0
	v_mov_b32_e32 v125, v0
	v_mov_b32_e32 v126, v0
	v_mov_b32_e32 v127, v0
.LBB0_954:
	ds_read_b128 v[144:147], v151
	ds_read_b128 v[156:159], v151 offset:1024
	ds_read_b128 v[160:163], v151 offset:2048
	ds_read_b128 v[164:167], v151 offset:3072
	ds_read_b128 v[168:171], v152
	ds_read_b128 v[172:175], v152 offset:1024
	ds_read_b128 v[176:179], v152 offset:2048
	ds_read_b128 v[180:183], v152 offset:3072
	s_add_u32 s36, s34, 0x3fe000
	s_addc_u32 s37, s35, 0
	s_cmp_eq_u32 s55, 60
	s_cselect_b32 s39, s25, s37
	s_cselect_b32 s38, s31, s36
	s_cselect_b32 s37, s23, s54
	s_cselect_b32 s36, s52, s53
	v_lshl_add_u64 v[216:217], s[34:35], 0, v[136:137]
	s_add_i32 m0, s33, 0xc000
	ds_read_b128 v[184:187], v153
	ds_read_b128 v[188:191], v153 offset:1024
	ds_read_b128 v[192:195], v153 offset:2048
	ds_read_b128 v[196:199], v153 offset:3072
	ds_read_b128 v[200:203], v153 offset:4096
	ds_read_b128 v[204:207], v153 offset:5120
	ds_read_b128 v[208:211], v153 offset:6144
	ds_read_b128 v[212:215], v153 offset:7168
	global_load_lds_dwordx4 v[216:217], off
	v_lshl_add_u64 v[216:217], s[34:35], 0, v[138:139]
	s_add_i32 m0, s33, 0xe000
	s_nop 0
	global_load_lds_dwordx4 v[216:217], off
	s_waitcnt vmcnt(8)
	s_waitcnt lgkmcnt(0)
	s_barrier
	s_setprio 1
	s_waitcnt lgkmcnt(0)
	v_mfma_f32_16x16x32_bf16 v[124:127], v[144:147], v[184:187], v[124:127]
	v_mfma_f32_16x16x32_bf16 v[120:123], v[160:163], v[184:187], v[120:123]
	v_mfma_f32_16x16x32_bf16 v[108:111], v[144:147], v[192:195], v[108:111]
	v_mfma_f32_16x16x32_bf16 v[104:107], v[160:163], v[192:195], v[104:107]
	v_mfma_f32_16x16x32_bf16 v[92:95], v[144:147], v[200:203], v[92:95]
	v_mfma_f32_16x16x32_bf16 v[88:91], v[160:163], v[200:203], v[88:91]
	v_mfma_f32_16x16x32_bf16 v[76:79], v[144:147], v[208:211], v[76:79]
	v_mfma_f32_16x16x32_bf16 v[72:75], v[160:163], v[208:211], v[72:75]
	v_mfma_f32_16x16x32_bf16 v[124:127], v[156:159], v[188:191], v[124:127]
	v_mfma_f32_16x16x32_bf16 v[120:123], v[164:167], v[188:191], v[120:123]
	v_mfma_f32_16x16x32_bf16 v[108:111], v[156:159], v[196:199], v[108:111]
	v_mfma_f32_16x16x32_bf16 v[104:107], v[164:167], v[196:199], v[104:107]
	v_mfma_f32_16x16x32_bf16 v[92:95], v[156:159], v[204:207], v[92:95]
	v_mfma_f32_16x16x32_bf16 v[88:91], v[164:167], v[204:207], v[88:91]
	v_mfma_f32_16x16x32_bf16 v[76:79], v[156:159], v[212:215], v[76:79]
	v_mfma_f32_16x16x32_bf16 v[72:75], v[164:167], v[212:215], v[72:75]
	s_setprio 0
	s_setprio 1
	v_mfma_f32_16x16x32_bf16 v[116:119], v[168:171], v[184:187], v[116:119]
	v_mfma_f32_16x16x32_bf16 v[112:115], v[176:179], v[184:187], v[112:115]
	v_mfma_f32_16x16x32_bf16 v[100:103], v[168:171], v[192:195], v[100:103]
	v_mfma_f32_16x16x32_bf16 v[96:99], v[176:179], v[192:195], v[96:99]
	v_mfma_f32_16x16x32_bf16 v[84:87], v[168:171], v[200:203], v[84:87]
	v_mfma_f32_16x16x32_bf16 v[80:83], v[176:179], v[200:203], v[80:83]
	v_mfma_f32_16x16x32_bf16 v[68:71], v[168:171], v[208:211], v[68:71]
	v_mfma_f32_16x16x32_bf16 v[64:67], v[176:179], v[208:211], v[64:67]
	v_mfma_f32_16x16x32_bf16 v[116:119], v[172:175], v[188:191], v[116:119]
	v_mfma_f32_16x16x32_bf16 v[112:115], v[180:183], v[188:191], v[112:115]
	v_mfma_f32_16x16x32_bf16 v[100:103], v[172:175], v[196:199], v[100:103]
	v_mfma_f32_16x16x32_bf16 v[96:99], v[180:183], v[196:199], v[96:99]
	v_mfma_f32_16x16x32_bf16 v[84:87], v[172:175], v[204:207], v[84:87]
	v_mfma_f32_16x16x32_bf16 v[80:83], v[180:183], v[204:207], v[80:83]
	v_mfma_f32_16x16x32_bf16 v[68:71], v[172:175], v[212:215], v[68:71]
	v_mfma_f32_16x16x32_bf16 v[64:67], v[180:183], v[212:215], v[64:67]
	s_setprio 0
	s_barrier
	s_add_i32 s56, s49, s3
	v_lshl_add_u64 v[216:217], s[36:37], 0, v[130:131]
	s_mov_b32 m0, s56
	ds_read_b128 v[184:187], v153 offset:16384
	ds_read_b128 v[188:191], v153 offset:17408
	ds_read_b128 v[192:195], v153 offset:18432
	ds_read_b128 v[196:199], v153 offset:19456
	ds_read_b128 v[200:203], v153 offset:20480
	ds_read_b128 v[204:207], v153 offset:21504
	ds_read_b128 v[208:211], v153 offset:22528
	ds_read_b128 v[212:215], v153 offset:23552
	global_load_lds_dwordx4 v[216:217], off
	s_add_i32 m0, s56, 0x2000
	s_add_u32 s56, s36, 0x100000
	v_lshl_add_u64 v[218:219], s[36:37], 0, v[134:135]
	s_addc_u32 s57, s37, 0
	s_add_i32 s58, s50, s3
	global_load_lds_dwordx4 v[218:219], off
	v_lshl_add_u64 v[222:223], s[56:57], 0, v[130:131]
	s_mov_b32 m0, s58
	v_lshl_add_u64 v[224:225], s[38:39], 0, v[132:133]
	global_load_lds_dwordx4 v[222:223], off
	v_lshl_add_u64 v[222:223], s[56:57], 0, v[134:135]
	s_add_i32 m0, s58, 0x2000
	s_nop 0
	global_load_lds_dwordx4 v[222:223], off
	v_lshl_add_u64 v[222:223], s[38:39], 0, v[128:129]
	s_mov_b32 m0, s33
	s_nop 0
	global_load_lds_dwordx4 v[222:223], off
	s_mov_b32 m0, s40
	s_nop 0
	global_load_lds_dwordx4 v[224:225], off
	s_waitcnt vmcnt(8)
	s_waitcnt lgkmcnt(0)
	s_barrier
	s_setprio 1
	s_waitcnt lgkmcnt(0)
	v_mfma_f32_16x16x32_bf16 v[60:63], v[144:147], v[184:187], v[60:63]
	v_mfma_f32_16x16x32_bf16 v[56:59], v[160:163], v[184:187], v[56:59]
	v_mfma_f32_16x16x32_bf16 v[44:47], v[144:147], v[192:195], v[44:47]
	v_mfma_f32_16x16x32_bf16 v[40:43], v[160:163], v[192:195], v[40:43]
	v_mfma_f32_16x16x32_bf16 v[28:31], v[144:147], v[200:203], v[28:31]
	v_mfma_f32_16x16x32_bf16 v[24:27], v[160:163], v[200:203], v[24:27]
	v_mfma_f32_16x16x32_bf16 v[12:15], v[144:147], v[208:211], v[12:15]
	v_mfma_f32_16x16x32_bf16 v[8:11], v[160:163], v[208:211], v[8:11]
	v_mfma_f32_16x16x32_bf16 v[60:63], v[156:159], v[188:191], v[60:63]
	v_mfma_f32_16x16x32_bf16 v[56:59], v[164:167], v[188:191], v[56:59]
	v_mfma_f32_16x16x32_bf16 v[44:47], v[156:159], v[196:199], v[44:47]
	v_mfma_f32_16x16x32_bf16 v[40:43], v[164:167], v[196:199], v[40:43]
	v_mfma_f32_16x16x32_bf16 v[28:31], v[156:159], v[204:207], v[28:31]
	v_mfma_f32_16x16x32_bf16 v[24:27], v[164:167], v[204:207], v[24:27]
	v_mfma_f32_16x16x32_bf16 v[12:15], v[156:159], v[212:215], v[12:15]
	v_mfma_f32_16x16x32_bf16 v[8:11], v[164:167], v[212:215], v[8:11]
	s_setprio 0
	s_setprio 1
	v_mfma_f32_16x16x32_bf16 v[52:55], v[168:171], v[184:187], v[52:55]
	v_mfma_f32_16x16x32_bf16 v[48:51], v[176:179], v[184:187], v[48:51]
	v_mfma_f32_16x16x32_bf16 v[36:39], v[168:171], v[192:195], v[36:39]
	v_mfma_f32_16x16x32_bf16 v[32:35], v[176:179], v[192:195], v[32:35]
	v_mfma_f32_16x16x32_bf16 v[20:23], v[168:171], v[200:203], v[20:23]
	v_mfma_f32_16x16x32_bf16 v[16:19], v[176:179], v[200:203], v[16:19]
	v_mfma_f32_16x16x32_bf16 v[4:7], v[168:171], v[208:211], v[4:7]
	v_mfma_f32_16x16x32_bf16 v[0:3], v[176:179], v[208:211], v[0:3]
	v_mfma_f32_16x16x32_bf16 v[52:55], v[172:175], v[188:191], v[52:55]
	v_mfma_f32_16x16x32_bf16 v[48:51], v[180:183], v[188:191], v[48:51]
	v_mfma_f32_16x16x32_bf16 v[36:39], v[172:175], v[196:199], v[36:39]
	v_mfma_f32_16x16x32_bf16 v[32:35], v[180:183], v[196:199], v[32:35]
	v_mfma_f32_16x16x32_bf16 v[20:23], v[172:175], v[204:207], v[20:23]
	v_mfma_f32_16x16x32_bf16 v[16:19], v[180:183], v[204:207], v[16:19]
	v_mfma_f32_16x16x32_bf16 v[4:7], v[172:175], v[212:215], v[4:7]
	v_mfma_f32_16x16x32_bf16 v[0:3], v[180:183], v[212:215], v[0:3]
	s_setprio 0
	s_barrier
	s_add_i32 s56, 0, 0x18000
	v_add_u32_e32 v155, s56, v149
	s_add_i32 s57, 0, 0x1c000
	ds_read_b128 v[144:147], v155
	ds_read_b128 v[156:159], v155 offset:1024
	ds_read_b128 v[160:163], v155 offset:2048
	ds_read_b128 v[164:167], v155 offset:3072
	v_add_u32_e32 v155, s57, v149
	ds_read_b128 v[168:171], v155
	ds_read_b128 v[172:175], v155 offset:1024
	ds_read_b128 v[176:179], v155 offset:2048
	ds_read_b128 v[180:183], v155 offset:3072
	s_add_u32 s38, s38, 0x2000
	s_addc_u32 s39, s39, 0
	s_mov_b32 m0, s41
	v_lshl_add_u64 v[226:227], s[38:39], 0, v[128:129]
	ds_read_b128 v[184:187], v153 offset:32768
	ds_read_b128 v[188:191], v153 offset:33792
	ds_read_b128 v[192:195], v153 offset:34816
	ds_read_b128 v[196:199], v153 offset:35840
	ds_read_b128 v[200:203], v153 offset:36864
	ds_read_b128 v[204:207], v153 offset:37888
	ds_read_b128 v[208:211], v153 offset:38912
	ds_read_b128 v[212:215], v153 offset:39936
	global_load_lds_dwordx4 v[226:227], off
	v_lshl_add_u64 v[226:227], s[38:39], 0, v[132:133]
	s_mov_b32 m0, s42
	s_nop 0
	global_load_lds_dwordx4 v[226:227], off
	s_waitcnt vmcnt(8)
	s_waitcnt lgkmcnt(0)
	s_barrier
	s_setprio 1
	s_waitcnt lgkmcnt(0)
	v_mfma_f32_16x16x32_bf16 v[124:127], v[144:147], v[184:187], v[124:127]
	v_mfma_f32_16x16x32_bf16 v[120:123], v[160:163], v[184:187], v[120:123]
	v_mfma_f32_16x16x32_bf16 v[108:111], v[144:147], v[192:195], v[108:111]
	v_mfma_f32_16x16x32_bf16 v[104:107], v[160:163], v[192:195], v[104:107]
	v_mfma_f32_16x16x32_bf16 v[92:95], v[144:147], v[200:203], v[92:95]
	v_mfma_f32_16x16x32_bf16 v[88:91], v[160:163], v[200:203], v[88:91]
	v_mfma_f32_16x16x32_bf16 v[76:79], v[144:147], v[208:211], v[76:79]
	v_mfma_f32_16x16x32_bf16 v[72:75], v[160:163], v[208:211], v[72:75]
	v_mfma_f32_16x16x32_bf16 v[124:127], v[156:159], v[188:191], v[124:127]
	v_mfma_f32_16x16x32_bf16 v[120:123], v[164:167], v[188:191], v[120:123]
	v_mfma_f32_16x16x32_bf16 v[108:111], v[156:159], v[196:199], v[108:111]
	v_mfma_f32_16x16x32_bf16 v[104:107], v[164:167], v[196:199], v[104:107]
	v_mfma_f32_16x16x32_bf16 v[92:95], v[156:159], v[204:207], v[92:95]
	v_mfma_f32_16x16x32_bf16 v[88:91], v[164:167], v[204:207], v[88:91]
	v_mfma_f32_16x16x32_bf16 v[76:79], v[156:159], v[212:215], v[76:79]
	v_mfma_f32_16x16x32_bf16 v[72:75], v[164:167], v[212:215], v[72:75]
	s_setprio 0
	s_setprio 1
	v_mfma_f32_16x16x32_bf16 v[116:119], v[168:171], v[184:187], v[116:119]
	v_mfma_f32_16x16x32_bf16 v[112:115], v[176:179], v[184:187], v[112:115]
	v_mfma_f32_16x16x32_bf16 v[100:103], v[168:171], v[192:195], v[100:103]
	v_mfma_f32_16x16x32_bf16 v[96:99], v[176:179], v[192:195], v[96:99]
	v_mfma_f32_16x16x32_bf16 v[84:87], v[168:171], v[200:203], v[84:87]
	v_mfma_f32_16x16x32_bf16 v[80:83], v[176:179], v[200:203], v[80:83]
	v_mfma_f32_16x16x32_bf16 v[68:71], v[168:171], v[208:211], v[68:71]
	v_mfma_f32_16x16x32_bf16 v[64:67], v[176:179], v[208:211], v[64:67]
	v_mfma_f32_16x16x32_bf16 v[116:119], v[172:175], v[188:191], v[116:119]
	v_mfma_f32_16x16x32_bf16 v[112:115], v[180:183], v[188:191], v[112:115]
	v_mfma_f32_16x16x32_bf16 v[100:103], v[172:175], v[196:199], v[100:103]
	v_mfma_f32_16x16x32_bf16 v[96:99], v[180:183], v[196:199], v[96:99]
	v_mfma_f32_16x16x32_bf16 v[84:87], v[172:175], v[204:207], v[84:87]
	v_mfma_f32_16x16x32_bf16 v[80:83], v[180:183], v[204:207], v[80:83]
	v_mfma_f32_16x16x32_bf16 v[68:71], v[172:175], v[212:215], v[68:71]
	v_mfma_f32_16x16x32_bf16 v[64:67], v[180:183], v[212:215], v[64:67]
	s_setprio 0
	s_barrier
	s_add_i32 s38, s56, s3
	v_lshl_add_u64 v[216:217], v[216:217], 0, s[18:19]
	s_mov_b32 m0, s38
	ds_read_b128 v[184:187], v153 offset:49152
	ds_read_b128 v[188:191], v153 offset:50176
	ds_read_b128 v[192:195], v153 offset:51200
	ds_read_b128 v[196:199], v153 offset:52224
	ds_read_b128 v[200:203], v153 offset:53248
	ds_read_b128 v[204:207], v153 offset:54272
	ds_read_b128 v[208:211], v153 offset:55296
	ds_read_b128 v[212:215], v153 offset:56320
	global_load_lds_dwordx4 v[216:217], off
	s_add_i32 m0, s38, 0x2000
	s_add_u32 s36, s36, 0x100080
	v_lshl_add_u64 v[216:217], v[218:219], 0, s[18:19]
	s_addc_u32 s37, s37, 0
	s_add_i32 s38, s57, s3
	global_load_lds_dwordx4 v[216:217], off
	v_lshl_add_u64 v[216:217], s[36:37], 0, v[130:131]
	s_mov_b32 m0, s38
	s_nop 0
	global_load_lds_dwordx4 v[216:217], off
	v_lshl_add_u64 v[216:217], s[36:37], 0, v[134:135]
	s_add_i32 m0, s38, 0x2000
	s_nop 0
	global_load_lds_dwordx4 v[216:217], off
	v_lshl_add_u64 v[216:217], v[222:223], 0, s[98:99]
	s_mov_b32 m0, s46
	s_nop 0
	global_load_lds_dwordx4 v[216:217], off
	v_lshl_add_u64 v[216:217], v[224:225], 0, s[98:99]
	s_mov_b32 m0, s47
	s_nop 0
	global_load_lds_dwordx4 v[216:217], off
	s_waitcnt vmcnt(8)
	s_waitcnt lgkmcnt(0)
	s_barrier
	s_setprio 1
	s_waitcnt lgkmcnt(0)
	v_mfma_f32_16x16x32_bf16 v[60:63], v[144:147], v[184:187], v[60:63]
	v_mfma_f32_16x16x32_bf16 v[56:59], v[160:163], v[184:187], v[56:59]
	v_mfma_f32_16x16x32_bf16 v[44:47], v[144:147], v[192:195], v[44:47]
	v_mfma_f32_16x16x32_bf16 v[40:43], v[160:163], v[192:195], v[40:43]
	v_mfma_f32_16x16x32_bf16 v[28:31], v[144:147], v[200:203], v[28:31]
	v_mfma_f32_16x16x32_bf16 v[24:27], v[160:163], v[200:203], v[24:27]
	v_mfma_f32_16x16x32_bf16 v[12:15], v[144:147], v[208:211], v[12:15]
	v_mfma_f32_16x16x32_bf16 v[8:11], v[160:163], v[208:211], v[8:11]
	v_mfma_f32_16x16x32_bf16 v[60:63], v[156:159], v[188:191], v[60:63]
	v_mfma_f32_16x16x32_bf16 v[56:59], v[164:167], v[188:191], v[56:59]
	v_mfma_f32_16x16x32_bf16 v[44:47], v[156:159], v[196:199], v[44:47]
	v_mfma_f32_16x16x32_bf16 v[40:43], v[164:167], v[196:199], v[40:43]
	v_mfma_f32_16x16x32_bf16 v[28:31], v[156:159], v[204:207], v[28:31]
	v_mfma_f32_16x16x32_bf16 v[24:27], v[164:167], v[204:207], v[24:27]
	v_mfma_f32_16x16x32_bf16 v[12:15], v[156:159], v[212:215], v[12:15]
	v_mfma_f32_16x16x32_bf16 v[8:11], v[164:167], v[212:215], v[8:11]
	s_setprio 0
	s_setprio 1
	v_mfma_f32_16x16x32_bf16 v[52:55], v[168:171], v[184:187], v[52:55]
	v_mfma_f32_16x16x32_bf16 v[48:51], v[176:179], v[184:187], v[48:51]
	v_mfma_f32_16x16x32_bf16 v[36:39], v[168:171], v[192:195], v[36:39]
	v_mfma_f32_16x16x32_bf16 v[32:35], v[176:179], v[192:195], v[32:35]
	v_mfma_f32_16x16x32_bf16 v[20:23], v[168:171], v[200:203], v[20:23]
	v_mfma_f32_16x16x32_bf16 v[16:19], v[176:179], v[200:203], v[16:19]
	v_mfma_f32_16x16x32_bf16 v[4:7], v[168:171], v[208:211], v[4:7]
	v_mfma_f32_16x16x32_bf16 v[0:3], v[176:179], v[208:211], v[0:3]
	v_mfma_f32_16x16x32_bf16 v[52:55], v[172:175], v[188:191], v[52:55]
	v_mfma_f32_16x16x32_bf16 v[48:51], v[180:183], v[188:191], v[48:51]
	v_mfma_f32_16x16x32_bf16 v[36:39], v[172:175], v[196:199], v[36:39]
	v_mfma_f32_16x16x32_bf16 v[32:35], v[180:183], v[196:199], v[32:35]
	v_mfma_f32_16x16x32_bf16 v[20:23], v[172:175], v[204:207], v[20:23]
	v_mfma_f32_16x16x32_bf16 v[16:19], v[180:183], v[204:207], v[16:19]
	v_mfma_f32_16x16x32_bf16 v[4:7], v[172:175], v[212:215], v[4:7]
	v_mfma_f32_16x16x32_bf16 v[0:3], v[180:183], v[212:215], v[0:3]
	s_setprio 0
	s_barrier
	s_add_i32 s55, s55, 2
	s_add_u32 s34, s34, 0x800000
	s_addc_u32 s35, s35, 0
	s_add_u32 s53, s53, 0x100
	s_addc_u32 s54, s54, 0
	s_cmp_gt_u32 s55, 61
	s_cbranch_scc0 .LBB0_954
	s_and_b64 vcc, exec, s[20:21]
	s_cbranch_vccz .LBB0_957
	s_barrier
